# HGRN scan staging waves: 64 idle slots after each data wait (conversion burst shifted off the compute waves' half start)
# baseline (speedup 1.0000x reference)
.Lscanh_loop:
	s_waitcnt vmcnt(9)
	s_nop 15
	s_nop 15
	s_nop 15
	s_nop 15
	v_lshlrev_b32_e32 v80, 16, v12
	v_and_b32_e32 v81, 0xffff0000, v12
	v_lshlrev_b32_e32 v82, 16, v16
	v_and_b32_e32 v83, 0xffff0000, v16
	v_lshlrev_b32_e32 v84, 16, v13
	v_and_b32_e32 v85, 0xffff0000, v13
	v_lshlrev_b32_e32 v86, 16, v17
	v_and_b32_e32 v87, 0xffff0000, v17
	v_mul_f32_e32 v80, v80, v82
	v_mul_f32_e32 v81, v81, v83
	v_mul_f32_e32 v84, v84, v86
	v_mul_f32_e32 v85, v85, v87
	v_cvt_pk_bf16_f32 v76, v80, v81
	v_cvt_pk_bf16_f32 v77, v84, v85
	v_lshlrev_b32_e32 v80, 16, v14
	v_and_b32_e32 v81, 0xffff0000, v14
	v_lshlrev_b32_e32 v82, 16, v18
	v_and_b32_e32 v83, 0xffff0000, v18
	v_lshlrev_b32_e32 v84, 16, v15
	v_and_b32_e32 v85, 0xffff0000, v15
	v_lshlrev_b32_e32 v86, 16, v19
	v_and_b32_e32 v87, 0xffff0000, v19
	v_mul_f32_e32 v80, v80, v82
	v_mul_f32_e32 v81, v81, v83
	v_mul_f32_e32 v84, v84, v86
	v_mul_f32_e32 v85, v85, v87
	v_cvt_pk_bf16_f32 v78, v80, v81
	v_cvt_pk_bf16_f32 v79, v84, v85
	v_lshlrev_b32_e32 v80, 16, v196
	v_and_b32_e32 v81, 0xffff0000, v196
	v_lshlrev_b32_e32 v82, 16, v200
	v_and_b32_e32 v83, 0xffff0000, v200
	v_lshlrev_b32_e32 v84, 16, v197
	v_and_b32_e32 v85, 0xffff0000, v197
	v_lshlrev_b32_e32 v86, 16, v201
	v_and_b32_e32 v87, 0xffff0000, v201
	v_mul_f32_e32 v80, v80, v82
	v_mul_f32_e32 v81, v81, v83
	v_mul_f32_e32 v84, v84, v86
	v_mul_f32_e32 v85, v85, v87
	v_cvt_pk_bf16_f32 v246, v80, v81
	v_cvt_pk_bf16_f32 v247, v84, v85
	v_lshlrev_b32_e32 v80, 16, v198
	v_and_b32_e32 v81, 0xffff0000, v198
	v_lshlrev_b32_e32 v82, 16, v202
	v_and_b32_e32 v83, 0xffff0000, v202
	v_lshlrev_b32_e32 v84, 16, v199
	v_and_b32_e32 v85, 0xffff0000, v199
	v_lshlrev_b32_e32 v86, 16, v203
	v_and_b32_e32 v87, 0xffff0000, v203
	v_mul_f32_e32 v80, v80, v82
	v_mul_f32_e32 v81, v81, v83
	v_mul_f32_e32 v84, v84, v86
	v_mul_f32_e32 v85, v85, v87
	v_cvt_pk_bf16_f32 v248, v80, v81
	v_cvt_pk_bf16_f32 v249, v84, v85
	ds_write_b128 v158, v[76:79]
	ds_write_b128 v158, v[20:23] offset:8704
	ds_write_b128 v158, v[24:27] offset:17408
	ds_write_b128 v228, v[246:249]
	ds_write_b128 v228, v[204:207] offset:8704
	ds_write_b128 v228, v[208:211] offset:17408
	s_and_saveexec_b64 s[14:15], s[2:3]
	ds_write_b128 v229, v[4:7] offset:26112
	s_or_b64 exec, exec, s[14:15]
	s_add_i32 s75, s76, 2
	s_cmpk_lt_u32 s76, 0x46
	s_cselect_b64 s[56:57], -1, 0
	s_cmpk_gt_u32 s76, 0x45
	s_cselect_b64 s[54:55], -1, 0
	s_waitcnt lgkmcnt(0)
	s_and_b64 vcc, exec, s[54:55]
	s_cbranch_vccnz .Lscanh_nopfax
	s_and_b64 vcc, exec, s[12:13]
	v_lshl_add_u32 v0, s75, 5, v113
	s_cbranch_vccnz .Lscanh_ia
	v_add3_u32 v1, v113, s74, 64
	v_cmp_lt_i32_e32 vcc, s47, v1
	s_and_saveexec_b64 s[14:15], vcc
	s_xor_b64 s[14:15], exec, s[14:15]
	v_add_u32_e32 v0, s38, v156
	v_add_u32_e32 v0, 0x9df, v0
	s_andn2_saveexec_b64 s[14:15], s[14:15]
	v_sub_u32_e32 v0, 0xff, v0
	s_or_b64 exec, exec, s[14:15]

.Lscanh_steady:
	s_waitcnt vmcnt(9)
	s_nop 15
	s_nop 15
	s_nop 15
	s_nop 15
	v_lshlrev_b32_e32 v80, 16, v28
	v_and_b32_e32 v81, 0xffff0000, v28
	v_lshlrev_b32_e32 v82, 16, v32
	v_and_b32_e32 v83, 0xffff0000, v32
	v_lshlrev_b32_e32 v84, 16, v29
	v_and_b32_e32 v85, 0xffff0000, v29
	v_lshlrev_b32_e32 v86, 16, v33
	v_and_b32_e32 v87, 0xffff0000, v33
	v_mul_f32_e32 v80, v80, v82
	v_mul_f32_e32 v81, v81, v83
	v_mul_f32_e32 v84, v84, v86
	v_mul_f32_e32 v85, v85, v87
	v_cvt_pk_bf16_f32 v68, v80, v81
	v_cvt_pk_bf16_f32 v69, v84, v85
	v_lshlrev_b32_e32 v80, 16, v30
	v_and_b32_e32 v81, 0xffff0000, v30
	v_lshlrev_b32_e32 v82, 16, v34
	v_and_b32_e32 v83, 0xffff0000, v34
	v_lshlrev_b32_e32 v84, 16, v31
	v_and_b32_e32 v85, 0xffff0000, v31
	v_lshlrev_b32_e32 v86, 16, v35
	v_and_b32_e32 v87, 0xffff0000, v35
	v_mul_f32_e32 v80, v80, v82
	v_mul_f32_e32 v81, v81, v83
	v_mul_f32_e32 v84, v84, v86
	v_mul_f32_e32 v85, v85, v87
	v_cvt_pk_bf16_f32 v70, v80, v81
	v_cvt_pk_bf16_f32 v71, v84, v85
	v_lshlrev_b32_e32 v80, 16, v212
	v_and_b32_e32 v81, 0xffff0000, v212
	v_lshlrev_b32_e32 v82, 16, v216
	v_and_b32_e32 v83, 0xffff0000, v216
	v_lshlrev_b32_e32 v84, 16, v213
	v_and_b32_e32 v85, 0xffff0000, v213
	v_lshlrev_b32_e32 v86, 16, v217
	v_and_b32_e32 v87, 0xffff0000, v217
	v_mul_f32_e32 v80, v80, v82
	v_mul_f32_e32 v81, v81, v83
	v_mul_f32_e32 v84, v84, v86
	v_mul_f32_e32 v85, v85, v87
	v_cvt_pk_bf16_f32 v246, v80, v81
	v_cvt_pk_bf16_f32 v247, v84, v85
	v_lshlrev_b32_e32 v80, 16, v214
	v_and_b32_e32 v81, 0xffff0000, v214
	v_lshlrev_b32_e32 v82, 16, v218
	v_and_b32_e32 v83, 0xffff0000, v218
	v_lshlrev_b32_e32 v84, 16, v215
	v_and_b32_e32 v85, 0xffff0000, v215
	v_lshlrev_b32_e32 v86, 16, v219
	v_and_b32_e32 v87, 0xffff0000, v219
	v_mul_f32_e32 v80, v80, v82
	v_mul_f32_e32 v81, v81, v83
	v_mul_f32_e32 v84, v84, v86
	v_mul_f32_e32 v85, v85, v87
	v_cvt_pk_bf16_f32 v248, v80, v81
	v_cvt_pk_bf16_f32 v249, v84, v85
	ds_write_b128 v158, v[68:71] offset:32768
	ds_write_b128 v158, v[36:39] offset:41472
	ds_write_b128 v158, v[40:43] offset:50176
	ds_write_b128 v228, v[246:249] offset:32768
	ds_write_b128 v228, v[220:223] offset:41472
	ds_write_b128 v228, v[224:227] offset:50176
	s_and_saveexec_b64 s[14:15], s[2:3]
	ds_write_b128 v229, v[8:11] offset:58880
	s_or_b64 exec, exec, s[14:15]
	s_waitcnt lgkmcnt(0)
	s_andn2_b64 vcc, exec, s[56:57]
	s_cbranch_vccnz .Lscanh_nopfbx
	s_lshl_b32 s14, s76, 5
	s_addk_i32 s14, 0x60
	s_and_b64 vcc, exec, s[12:13]
	v_add_u32_e32 v0, s14, v113
	s_cbranch_vccnz .Lscanh_ib
	v_add_u32_e32 v1, s74, v113
	v_add_u32_e32 v1, 0x60, v1
	v_cmp_lt_i32_e32 vcc, s47, v1
	s_and_saveexec_b64 s[14:15], vcc
	s_xor_b64 s[14:15], exec, s[14:15]
	v_add_u32_e32 v0, s38, v156
	v_add_u32_e32 v0, 0x9bf, v0
	s_andn2_saveexec_b64 s[14:15], s[14:15]
	v_sub_u32_e32 v0, 0xff, v0
	s_or_b64 exec, exec, s[14:15]
